# grid barrier: non-leader workgroups poll the top-level generation word directly instead of the per-XCD generation (one hand-off hop less)
# speedup vs baseline: 1.0265x; 1.0026x over previous
.LBB0_938:
	s_or_b64 exec, exec, s[2:3]
	s_waitcnt vmcnt(0)
	v_readfirstlane_b32 s2, v3
	v_sub_u32_e32 v4, 0, v2
	s_nop 0
	v_add_u32_e32 v3, s2, v1
	v_cvt_f32_u32_e32 v1, v2
	v_rcp_iflag_f32_e32 v1, v1
	s_nop 0
	v_mul_f32_e32 v1, 0x4f7ffffe, v1
	v_cvt_u32_f32_e32 v1, v1
	v_mul_lo_u32 v4, v4, v1
	v_mul_hi_u32 v4, v1, v4
	v_add_u32_e32 v1, v1, v4
	v_mul_hi_u32 v1, v3, v1
	v_mul_lo_u32 v4, v1, v2
	v_sub_u32_e32 v4, v3, v4
	v_cmp_ge_u32_e32 vcc, v4, v2
	v_add_u32_e32 v5, 1, v1
	s_nop 0
	v_cndmask_b32_e32 v1, v1, v5, vcc
	v_sub_u32_e32 v5, v4, v2
	v_cndmask_b32_e32 v4, v4, v5, vcc
	v_cmp_ge_u32_e32 vcc, v4, v2
	v_add_u32_e32 v4, 1, v1
	s_nop 0
	v_cndmask_b32_e32 v1, v1, v4, vcc
	v_add_u32_e32 v4, 1, v3
	v_mad_u64_u32 v[2:3], s[2:3], v2, v1, v[2:3]
	v_cmp_ne_u32_e32 vcc, v4, v2
	s_and_saveexec_b64 s[2:3], vcc
	s_xor_b64 s[2:3], exec, s[2:3]
	s_cbranch_execz .LBB0_952
	v_readlane_b32 s16, v253, 0
	v_readlane_b32 s17, v253, 1
	s_nop 4
	global_load_dword v0, v129, s[16:17] sc1
	s_waitcnt vmcnt(0)
	v_cmp_eq_u32_e32 vcc, v0, v1
	s_and_saveexec_b64 s[24:25], vcc
	s_cbranch_execz .LBB0_951
	s_mov_b32 s42, 1
	s_mov_b64 s[26:27], 0
	s_branch .LBB0_942

.LBB0_944:
	v_readlane_b32 s16, v253, 0
	v_readlane_b32 s17, v253, 1
	s_add_i32 s42, s42, 1
	s_mov_b64 s[38:39], -1
	s_nop 2
	global_load_dword v0, v129, s[16:17] sc1
	s_waitcnt vmcnt(0)
	v_cmp_ne_u32_e32 vcc, v0, v1
	s_orn2_b64 s[36:37], vcc, exec
	s_branch .LBB0_941
